# plus RWKV Sw=S*w+k*v precompute in DPP slots, SGU inner loop LDS reads hoisted
# speedup vs baseline: 1.0185x; 1.0050x over previous
; #define LAS __attribute__((address_space(3)))
; __device__ __forceinline__ void sgu_job(LAS unsigned char* lds, const GAS float* Wh, const GAS float* sbias, const GAS float* VLN, GAS float* U, int m0, int h, int tid) {
;     ...
;     for (int s = 0; s <= t0 + 3; ++s) {
;         const f32x4 v0 = *(const LAS f32x4*)(VT + s * 128 + d0), v1 = *(const LAS f32x4*)(VT + s * 128 + d0 + 4);
; #pragma unroll
;         for (int i = 0; i < 4; ++i) { const float w = WL[(t0 + i) * 132 + s];
;             acc[i][0] += w * v0.x; acc[i][1] += w * v0.y; acc[i][2] += w * v0.z; acc[i][3] += w * v0.w; acc[i][4] += w * v1.x; acc[i][5] += w * v1.y; acc[i][6] += w * v1.z; acc[i][7] += w * v1.w; }
;     }
.LBB0_624:
	v_add_u32_e32 v149, -16, v44
	ds_read_b128 v[150:153], v149
	ds_read_b128 v[154:157], v44
	ds_read2_b32 v[158:159], v45 offset1:132
	ds_read_b32 v162, v45 offset:1056
	ds_read_b32 v163, v147
	v_add_u32_e32 v148, -1, v148
	v_cmp_eq_u32_e32 vcc, 0, v148
	v_add_u32_e32 v44, 0x200, v44
	v_add_u32_e32 v45, 4, v45
	v_add_u32_e32 v147, 4, v147
	s_or_b64 s[0:1], vcc, s[0:1]
	s_waitcnt lgkmcnt(0)
	v_pk_fma_f32 v[40:41], v[150:151], v[158:159], v[40:41] op_sel_hi:[1,0,1]
	v_pk_fma_f32 v[42:43], v[152:153], v[158:159], v[42:43] op_sel_hi:[1,0,1]
	v_pk_fma_f32 v[36:37], v[154:155], v[158:159], v[36:37] op_sel_hi:[1,0,1]
	v_pk_fma_f32 v[38:39], v[156:157], v[158:159], v[38:39] op_sel_hi:[1,0,1]
	v_pk_fma_f32 v[34:35], v[150:151], v[158:159], v[34:35] op_sel:[0,1,0]
	v_pk_fma_f32 v[32:33], v[152:153], v[158:159], v[32:33] op_sel:[0,1,0]
	v_pk_fma_f32 v[30:31], v[154:155], v[158:159], v[30:31] op_sel:[0,1,0]
	v_pk_fma_f32 v[28:29], v[156:157], v[158:159], v[28:29] op_sel:[0,1,0]
	v_pk_fma_f32 v[26:27], v[150:151], v[162:163], v[26:27] op_sel_hi:[1,0,1]
	v_pk_fma_f32 v[24:25], v[152:153], v[162:163], v[24:25] op_sel_hi:[1,0,1]
	v_pk_fma_f32 v[22:23], v[154:155], v[162:163], v[22:23] op_sel_hi:[1,0,1]
	v_pk_fma_f32 v[20:21], v[156:157], v[162:163], v[20:21] op_sel_hi:[1,0,1]
	v_pk_fma_f32 v[18:19], v[150:151], v[162:163], v[18:19] op_sel:[0,1,0]
	v_pk_fma_f32 v[14:15], v[152:153], v[162:163], v[14:15] op_sel:[0,1,0]
	v_pk_fma_f32 v[12:13], v[154:155], v[162:163], v[12:13] op_sel:[0,1,0]
	v_pk_fma_f32 v[10:11], v[156:157], v[162:163], v[10:11] op_sel:[0,1,0]
	s_andn2_b64 exec, exec, s[0:1]
	s_cbranch_execnz .LBB0_624
	s_or_b64 exec, exec, s[0:1]
	s_branch .LBB0_621

; #define LAS __attribute__((address_space(3)))
; #define R4_ISSUE(cc, slot) do { const GAS float* g_ = gp + (size_t)(cc) * 2048; LAS float* l_ = ring + (slot) * 1536; _Pragma("unroll") for (int i_ = 0; i_ < 6; ++i_) \
;         __builtin_amdgcn_global_load_lds((const GAS unsigned*)(g_ + off[i_]), (LAS unsigned*)(l_ + i_ * 256), 16, 0, 0); } while (0)
; #define R4_LOAD(o, sb_) do { const LAS float* sb = (sb_); (o).r = *(const LAS f32x4*)(sb + cgp * 4); (o).w = *(const LAS f32x4*)(sb + 64 + cgp * 4); (o).k = *(const LAS f32x4*)(sb + 128 + cgp * 4); \
;         (o).a = *(const LAS f32x4*)(sb + 256 + cgp * 4); (o).b = *(const LAS f32x4*)(sb + 320 + cgp * 4); (o).vv = sb[192 + rq * 4 + rl]; asm volatile("" ::: "memory"); } while (0)
; __device__ __forceinline__ void rwkv_prompt_wave4(LAS float* ring, const GAS float* RW, int mbase, int h, int rq, GAS float* Sout, GAS float* YR, int lane) {
;     ...
;     for (int cc = 0; cc < 3; ++cc) R4_ISSUE(cc, cc);
;     float ykeep = 0.f;
;     R4Ops oA, oB, oC, oD;
;     asm volatile("s_waitcnt vmcnt(12)" ::: "memory");
;     R4_LOAD(oA, ring); R4_LOAD(oB, ring + 384);
;     for (int ci = 0; ci < NCH; ++ci) {
;         { const int cn = ci + 3; const int cl = cn < NCH ? cn : NCH - 1; R4_ISSUE(cl, cn % R4_NS); }
;         const LAS float* cb = ring + (ci % R4_NS) * 1536; const LAS float* nb = ring + ((ci + 1) % R4_NS) * 1536;
;         R4_LOAD(oC, cb + 768);  R4_STEP(oA, 0);
;         R4_LOAD(oD, cb + 1152); R4_STEP(oB, 1);
;         asm volatile("s_waitcnt vmcnt(12)" ::: "memory");
;         R4_LOAD(oA, nb);        R4_STEP(oC, 2);
;         R4_LOAD(oB, nb + 384);  R4_STEP(oD, 3);
;         if (cgp < 4) YR[(size_t)(mbase + ci * 4 + cgp) * 512 + h * 64 + rq * 4 + rl] = ykeep;
.LBB0_707:
	s_barrier
	s_lshr_b32 s0, s20, 4
	s_mul_i32 s0, s0, 0x18000
	v_subrev_u32_e32 v63, s0, v70
	v_subrev_u32_e32 v109, s0, v67
	s_lshr_b32 s0, s21, 4
	s_mul_i32 s0, s0, 0x18000
	v_subrev_u32_e32 v88, s0, v70
	v_subrev_u32_e32 v74, s0, v67
	s_waitcnt lgkmcnt(6)
	v_pk_mul_f32 v[28:29], v[44:45], v[28:29]
	s_add_i32 s0, s14, s19
	v_pk_fma_f32 v[26:27], v[42:43], v[26:27], v[28:29]
	v_add_u32_e32 v104, s0, v74
	v_add_f32_e32 v26, v26, v27
	ds_read_b128 v[72:75], v104 offset:3072
	ds_read_b128 v[76:79], v104 offset:3328
	v_add_f32_dpp v26, v26, v26 quad_perm:[1,0,3,2] row_mask:0xf bank_mask:0xf bound_ctrl:1
	ds_read_b128 v[80:83], v104 offset:3584
	ds_read_b128 v[84:87], v104 offset:4096
	v_add_f32_dpp v26, v26, v26 quad_perm:[2,3,0,1] row_mask:0xf bank_mask:0xf bound_ctrl:1
	v_pk_mul_f32 v[8:9], v[64:65], v[8:9] op_sel_hi:[0,1]
	v_pk_mul_f32 v[10:11], v[64:65], v[10:11] op_sel_hi:[0,1]
	v_add_f32_dpp v26, v26, v26 row_half_mirror row_mask:0xf bank_mask:0xf bound_ctrl:1
	v_pk_fma_f32 v[4:5], v[42:43], v[4:5], v[8:9]
	v_pk_fma_f32 v[6:7], v[44:45], v[6:7], v[10:11]
	v_add_f32_dpp v26, v26, v26 row_mirror row_mask:0xf bank_mask:0xf bound_ctrl:1
	v_add_u32_e32 v110, s0, v88
	v_pk_fma_f32 v[4:5], v[22:23], v[26:27], v[4:5] op_sel_hi:[1,0,1]
	v_pk_fma_f32 v[6:7], v[24:25], v[26:27], v[6:7] op_sel_hi:[1,0,1]
	ds_read_b128 v[88:91], v104 offset:4352
	ds_read_b32 v108, v110 offset:3840
	ds_read_b128 v[92:95], v104 offset:4608
	ds_read_b128 v[42:45], v104 offset:4864
	ds_read_b128 v[96:99], v104 offset:5120
	ds_read_b128 v[100:103], v104 offset:5632
	ds_read_b128 v[104:107], v104 offset:5888
	ds_read_b32 v110, v110 offset:5376
	s_waitcnt lgkmcnt(12)
	v_pk_mul_f32 v[2:3], v[2:3], v[6:7]
	v_pk_mul_f32 v[40:41], v[40:41], v[6:7]
	v_add_u32_e32 v63, s0, v63
	v_pk_fma_f32 v[0:1], v[0:1], v[4:5], v[2:3]
	v_pk_fma_f32 v[38:39], v[38:39], v[4:5], v[40:41]
	v_add_f32_e32 v0, v0, v1
	v_pk_mul_f32 v[30:31], v[66:67], v[30:31] op_sel_hi:[0,1]
	v_add_f32_e32 v38, v38, v39
	v_pk_mul_f32 v[32:33], v[66:67], v[32:33] op_sel_hi:[0,1]
	v_add_f32_dpp v0, v0, v0 quad_perm:[1,0,3,2] row_mask:0xf bank_mask:0xf bound_ctrl:1
	v_add_f32_dpp v38, v38, v38 quad_perm:[1,0,3,2] row_mask:0xf bank_mask:0xf bound_ctrl:1
	v_pk_fma_f32 v[18:19], v[18:19], v[4:5], v[30:31]
	v_add_f32_dpp v0, v0, v0 quad_perm:[2,3,0,1] row_mask:0xf bank_mask:0xf bound_ctrl:1
	v_add_f32_dpp v38, v38, v38 quad_perm:[2,3,0,1] row_mask:0xf bank_mask:0xf bound_ctrl:1
	v_pk_fma_f32 v[20:21], v[20:21], v[6:7], v[32:33]
	v_add_f32_dpp v0, v0, v0 row_half_mirror row_mask:0xf bank_mask:0xf bound_ctrl:1
	v_add_f32_dpp v38, v38, v38 row_half_mirror row_mask:0xf bank_mask:0xf bound_ctrl:1
	s_nop 0
	v_add_f32_dpp v0, v0, v0 row_mirror row_mask:0xf bank_mask:0xf bound_ctrl:1
	v_add_f32_dpp v38, v38, v38 row_mirror row_mask:0xf bank_mask:0xf bound_ctrl:1
	v_cndmask_b32_e32 v8, v71, v0, vcc
	v_pk_fma_f32 v[20:21], v[36:37], v[38:39], v[20:21] op_sel_hi:[1,0,1]
	v_pk_fma_f32 v[18:19], v[34:35], v[38:39], v[18:19] op_sel_hi:[1,0,1]
	v_pk_mul_f32 v[0:1], v[14:15], v[20:21]
	v_add_u32_e32 v34, s0, v109
	v_pk_fma_f32 v[0:1], v[12:13], v[18:19], v[0:1]
	s_waitcnt lgkmcnt(0)
	v_pk_mul_f32 v[12:13], v[86:87], v[20:21]
	v_add_f32_e32 v0, v0, v1
	v_pk_fma_f32 v[12:13], v[84:85], v[18:19], v[12:13]
	v_pk_mul_f32 v[80:81], v[80:81], v[108:109] op_sel_hi:[1,0]
	v_add_f32_e32 v12, v12, v13
	v_add_f32_dpp v0, v0, v0 quad_perm:[1,0,3,2] row_mask:0xf bank_mask:0xf bound_ctrl:1
	v_pk_mul_f32 v[82:83], v[82:83], v[108:109] op_sel_hi:[1,0]
	v_add_f32_dpp v12, v12, v12 quad_perm:[1,0,3,2] row_mask:0xf bank_mask:0xf bound_ctrl:1
	v_add_f32_dpp v0, v0, v0 quad_perm:[2,3,0,1] row_mask:0xf bank_mask:0xf bound_ctrl:1
	v_pk_fma_f32 v[76:77], v[76:77], v[18:19], v[80:81]
	v_add_f32_dpp v12, v12, v12 quad_perm:[2,3,0,1] row_mask:0xf bank_mask:0xf bound_ctrl:1
	v_add_f32_dpp v0, v0, v0 row_half_mirror row_mask:0xf bank_mask:0xf bound_ctrl:1
	v_pk_fma_f32 v[78:79], v[78:79], v[20:21], v[82:83]
	v_add_f32_dpp v12, v12, v12 row_half_mirror row_mask:0xf bank_mask:0xf bound_ctrl:1
	v_add_f32_dpp v0, v0, v0 row_mirror row_mask:0xf bank_mask:0xf bound_ctrl:1
	v_cndmask_b32_e64 v30, v8, v0, s[4:5]
	v_add_f32_dpp v12, v12, v12 row_mirror row_mask:0xf bank_mask:0xf bound_ctrl:1
	v_pk_fma_f32 v[76:77], v[88:89], v[12:13], v[76:77] op_sel_hi:[1,0,1]
	v_pk_fma_f32 v[78:79], v[90:91], v[12:13], v[78:79] op_sel_hi:[1,0,1]
	ds_read_b128 v[0:3], v34 offset:6144
	v_pk_mul_f32 v[12:13], v[74:75], v[78:79]
	ds_read_b128 v[4:7], v34 offset:6400
	v_pk_fma_f32 v[12:13], v[72:73], v[76:77], v[12:13]
	ds_read_b128 v[8:11], v34 offset:6656
	v_pk_mul_f32 v[72:73], v[102:103], v[78:79]
	v_add_f32_e32 v12, v12, v13
	v_pk_fma_f32 v[72:73], v[100:101], v[76:77], v[72:73]
	ds_read_b128 v[26:29], v34 offset:7168
	v_add_f32_e32 v72, v72, v73
	ds_read_b128 v[22:25], v34 offset:7424
	v_add_f32_dpp v12, v12, v12 quad_perm:[1,0,3,2] row_mask:0xf bank_mask:0xf bound_ctrl:1
	ds_read_b32 v64, v63 offset:6912
	v_add_f32_dpp v72, v72, v72 quad_perm:[1,0,3,2] row_mask:0xf bank_mask:0xf bound_ctrl:1
	v_pk_mul_f32 v[96:97], v[96:97], v[110:111] op_sel_hi:[1,0]
	v_add_f32_dpp v12, v12, v12 quad_perm:[2,3,0,1] row_mask:0xf bank_mask:0xf bound_ctrl:1
	v_add_f32_dpp v72, v72, v72 quad_perm:[2,3,0,1] row_mask:0xf bank_mask:0xf bound_ctrl:1
	v_pk_mul_f32 v[98:99], v[98:99], v[110:111] op_sel_hi:[1,0]
	v_add_f32_dpp v12, v12, v12 row_half_mirror row_mask:0xf bank_mask:0xf bound_ctrl:1
	v_add_f32_dpp v72, v72, v72 row_half_mirror row_mask:0xf bank_mask:0xf bound_ctrl:1
	v_pk_fma_f32 v[42:43], v[42:43], v[76:77], v[96:97]
	v_add_f32_dpp v12, v12, v12 row_mirror row_mask:0xf bank_mask:0xf bound_ctrl:1
	v_add_f32_dpp v72, v72, v72 row_mirror row_mask:0xf bank_mask:0xf bound_ctrl:1
	v_pk_fma_f32 v[44:45], v[44:45], v[78:79], v[98:99]
	v_cndmask_b32_e64 v71, v30, v12, s[6:7]
	v_pk_fma_f32 v[42:43], v[104:105], v[72:73], v[42:43] op_sel_hi:[1,0,1]
	v_pk_fma_f32 v[44:45], v[106:107], v[72:73], v[44:45] op_sel_hi:[1,0,1]
	ds_read_b128 v[12:15], v34 offset:7680
	v_pk_mul_f32 v[72:73], v[94:95], v[44:45]
	ds_read_b128 v[18:21], v34 offset:7936
	v_pk_fma_f32 v[72:73], v[92:93], v[42:43], v[72:73]
	ds_read_b128 v[30:33], v34 offset:8192
	v_add_f32_e32 v72, v72, v73
	ds_read_b128 v[38:41], v34 offset:8704
	ds_read_b128 v[34:37], v34 offset:8960
	v_add_f32_dpp v72, v72, v72 quad_perm:[1,0,3,2] row_mask:0xf bank_mask:0xf bound_ctrl:1
	ds_read_b32 v66, v63 offset:8448
	s_nop 0
	v_add_f32_dpp v72, v72, v72 quad_perm:[2,3,0,1] row_mask:0xf bank_mask:0xf bound_ctrl:1
	s_nop 1
	v_add_f32_dpp v72, v72, v72 row_half_mirror row_mask:0xf bank_mask:0xf bound_ctrl:1
	s_nop 1
	v_add_f32_dpp v72, v72, v72 row_mirror row_mask:0xf bank_mask:0xf bound_ctrl:1
	v_cndmask_b32_e64 v71, v71, v72, s[8:9]
	s_and_saveexec_b64 s[0:1], s[40:41]
	s_cbranch_execz .LBB0_706
	v_ashrrev_i32_e32 v63, 31, v62
	v_lshlrev_b64 v[72:73], 11, v[62:63]
	v_lshl_add_u64 v[72:73], v[60:61], 0, v[72:73]
	global_store_dword v[72:73], v71, off
	s_branch .LBB0_706
